# lever 2: scan item prologue de-serialised (conv-weight and chunk-0 a_cs/dt LDS stores deferred to the single pre-loop drain)
# baseline (speedup 1.0000x reference)
; DI void ssd_scan_phase(bf16_t* P, const bf16_t* BT, const bf16_t* Cc, const bf16_t* CB, const float* dt, const float* acs,
;                        const float* cw, const float* cb, const float* Dp, char* lds, bool dry, int mode, float* Sbuf) {
;     ...
;     if (tid < 160) sCw[tid] = (tid < 128) ? cw[(tid >> 5) * 3072 + pcol + (tid & 31)] : cb[pcol + tid - 128];
.LBB0_1026:
	s_or_b64 exec, exec, s[70:71]
	s_waitcnt vmcnt(1)
	global_load_dword v47, v[2:3], off

; DI void ssd_scan_phase(bf16_t* P, const bf16_t* BT, const bf16_t* Cc, const bf16_t* CB, const float* dt, const float* acs,
;                        const float* cw, const float* cb, const float* Dp, char* lds, bool dry, int mode, float* Sbuf) {
;     ...
;       const float* aq = acs + tbs * 32 + hh; const float* dq = dt + tbs * 32 + hh;
;       if (tid < 128) { sAcs[tid] = aq[tid * 32]; sDt[tid] = dq[tid * 32]; racs = aq[4096 + tid * 32]; rdt = dq[4096 + tid * 32]; }
;     }
;     __syncthreads();
.LBB0_1051:
	s_or_b64 exec, exec, s[78:79]
	v_mov_b32_e32 v195, 0
	v_mov_b32_e32 v194, 0
	s_and_saveexec_b64 s[78:79], s[48:49]
	s_cbranch_execz .LBB0_1053
	s_lshl_b64 s[72:73], s[72:73], 7
	s_add_u32 s69, s24, s72
	s_addc_u32 s75, s25, s73
	s_add_u32 s82, s69, s74
	s_addc_u32 s83, s75, 0
	s_add_u32 s69, s26, s72
	s_addc_u32 s73, s27, s73
	s_add_u32 s72, s69, s74
	s_addc_u32 s73, s73, 0
	v_lshl_add_u64 v[20:21], s[72:73], 0, v[148:149]
	global_load_dword v49, v[20:21], off
	v_add_co_u32_e32 v20, vcc, 0x4000, v20
	v_lshl_add_u64 v[22:23], s[82:83], 0, v[148:149]
	v_addc_co_u32_e32 v21, vcc, 0, v21, vcc
	global_load_dword v194, v[20:21], off
	v_add_co_u32_e32 v20, vcc, 0x4000, v22
	global_load_dword v50, v[22:23], off
	s_nop 0
	v_addc_co_u32_e32 v21, vcc, 0, v23, vcc
	global_load_dword v195, v[20:21], off
.LBB0_1053:
	s_or_b64 exec, exec, s[78:79]
	v_readlane_b32 s4, v253, 16
	s_add_i32 s69, s80, s28
	v_readlane_b32 s18, v253, 30
	v_readlane_b32 s19, v253, 31
	s_add_u32 s72, s18, s34
	v_readlane_b32 s16, v253, 28
	s_addc_u32 s73, s19, 0
	s_mov_b32 s75, s35
	v_lshl_add_u64 v[20:21], v[124:125], 0, s[76:77]
	s_lshl_b64 s[76:77], s[80:81], 17
	v_readlane_b32 s17, v253, 29
	v_lshl_add_u64 v[164:165], v[150:151], 0, s[74:75]
	v_lshl_add_u64 v[166:167], v[152:153], 0, s[74:75]
	s_add_u32 s74, s16, s76
	s_addc_u32 s75, s17, s77
	s_add_u32 s76, s20, s76
	s_addc_u32 s77, s21, s77
	s_lshl_b32 s78, s80, 13
	s_add_i32 s85, s78, 0x2000
	s_lshl_b32 s78, s80, 7
	s_waitcnt vmcnt(0)
	v_mov_b32_e32 v157, v156
	v_lshlrev_b64 v[168:169], 1, v[20:21]
	v_mov_b32_e32 v170, s78
	v_lshlrev_b32_e32 v46, 4, v200
	v_mov_b32_e32 v36, 0
	v_mov_b32_e32 v37, 0
	v_mov_b32_e32 v38, 0
	v_mov_b32_e32 v39, 0
	ds_write_b128 v46, v[36:39]
	ds_write_b128 v46, v[36:39] offset:8192
	ds_write_b128 v46, v[36:39] offset:16384
	ds_write_b128 v46, v[36:39] offset:24576
	s_and_saveexec_b64 s[78:79], s[46:47]
	ds_write_b32 v182, v47
	s_or_b64 exec, exec, s[78:79]
	s_and_saveexec_b64 s[78:79], s[48:49]
	ds_write_b32 v184, v49
	ds_write_b32 v185, v50
	s_or_b64 exec, exec, s[78:79]
	s_waitcnt lgkmcnt(0)
	s_barrier
	v_readlane_b32 s5, v253, 17
	v_readlane_b32 s6, v253, 18
	v_readlane_b32 s7, v253, 19
	v_readlane_b32 s8, v253, 20
	v_readlane_b32 s9, v253, 21
	v_readlane_b32 s10, v253, 22
	v_readlane_b32 s11, v253, 23
	v_readlane_b32 s12, v253, 24
	v_readlane_b32 s13, v253, 25
	v_readlane_b32 s14, v253, 26
	v_readlane_b32 s15, v253, 27
